# phase_dt: 32 loads in flight instead of load-wait-mfma chain; tiles spread over all workgroups
# speedup vs baseline: 1.0215x; 1.0043x over previous
; #define TIDX opaque_tid()
; __device__ void phase_dt(const Params& p, int l) {
;     const int tid = TIDX, wid = tid >> 6, lane = tid & 63, fr = lane & 15, fq = lane >> 4;
;     const bf16_t* xb = (const bf16_t*)(p.ws + W_XB); const bf16_t* wdt = (const bf16_t*)(p.ws + W_WDT) + (size_t)l * 16 * DM;
;     const u64* rss = (const u64*)(p.ws + W_RSS) + (size_t)(2 * l) * TT; float* dtraw = (float*)(p.ws + W_DT);
;     for (int tile = blockIdx.x * 8 + wid; tile < TT / 16; tile += gridDim.x * 8) {
;         const bf16_t* ap = xb + (size_t)(tile * 16 + fr) * DM + 8 * fq; const bf16_t* bp = wdt + (size_t)fr * DM + 8 * fq;
.LBB0_510:
	v_mov_b32_e32 v0, v163
	v_readlane_b32 s0, v250, 4
	v_ashrrev_i32_e32 v2, 6, v0
	s_nop 1
	s_lshr_b32 s0, s0, 3
	v_mov_b32_e32 v20, s0
	v_mad_u32_u24 v20, v2, s94, v20
	s_movk_i32 s0, 0x408
	v_cmp_gt_i32_e32 vcc, s0, v20
	s_and_saveexec_b64 s[38:39], vcc
	s_cbranch_execz .LBB0_517
	v_readlane_b32 s0, v254, 48
	v_and_b32_e32 v21, 15, v0
	v_readlane_b32 s1, v254, 49
	v_bfe_u32 v0, v0, 4, 2
	v_lshlrev_b32_e32 v2, 4, v2
	v_readlane_b32 s24, v253, 48
	s_lshl_b64 s[2:3], s[0:1], 15
	v_cmp_gt_u32_e64 s[0:1], 2, v0
	v_lshlrev_b32_e32 v0, 4, v0
	v_lshl_add_u32 v10, v20, 4, v21
	v_lshlrev_b32_e32 v2, 11, v21
	v_readlane_b32 s40, v250, 49
	v_or3_b32 v2, s2, v2, v0
	v_mov_b32_e32 v3, s3
	v_readlane_b32 s2, v253, 52
	v_readlane_b32 s41, v250, 50
	v_readlane_b32 s3, v253, 53
	v_lshl_add_u64 v[8:9], s[88:89], 0, v[0:1]
	v_lshl_add_u64 v[6:7], s[40:41], 0, v[0:1]
	v_lshl_add_u64 v[12:13], s[2:3], 0, v[2:3]
	s_mov_b64 s[40:41], 0
	s_branch .LBB0_513

; __device__ __forceinline__ float rstd_fix(u64 v) { return rsqrtf((float)v * (1.f / (1048576.f * 1024.f)) + 1e-6f); }
; #define MFMA(X, Y, C) __builtin_amdgcn_mfma_f32_16x16x32_bf16((X), (Y), (C), 0, 0, 0)
; __device__ void phase_dt(const Params& p, int l) {
;     ...
;     for (int tile = blockIdx.x * 8 + wid; tile < TT / 16; tile += gridDim.x * 8) {
;         const bf16_t* ap = xb + (size_t)(tile * 16 + fr) * DM + 8 * fq; const bf16_t* bp = wdt + (size_t)fr * DM + 8 * fq;
;         f32x4 acc = {0.f, 0.f, 0.f, 0.f};
; #pragma unroll 16
;         for (int s = 0; s < 32; ++s) acc = MFMA(*(const bf16x8*)(bp + 32 * s), *(const bf16x8*)(ap + 32 * s), acc);
;         const int row = tile * 16 + fr;
;         if (fq < 2) { const float rs = rstd_fix(rss[row]); *(f32x4*)(dtraw + (size_t)row * 8 + 4 * fq) = acc * rs; }
.LBB0_514:
	v_lshl_add_u64 v[18:19], v[12:13], 0, s[42:43]
	v_lshl_add_u64 v[16:17], v[14:15], 0, s[42:43]
	v_add_co_u32_e32 v16, vcc, 0xa2a5000, v16
	s_add_u32 s42, s42, 0x400
	s_nop 0
	v_addc_co_u32_e32 v17, vcc, 0, v17, vcc
	s_addc_u32 s43, s43, 0
	s_waitcnt lgkmcnt(0)
	global_load_dwordx4 v[30:33], v[18:19], off offset:-512
	global_load_dwordx4 v[34:37], v[16:17], off offset:1536
	global_load_dwordx4 v[38:41], v[18:19], off offset:-448
	global_load_dwordx4 v[42:45], v[16:17], off offset:1600
	global_load_dwordx4 v[46:49], v[18:19], off offset:-384
	global_load_dwordx4 v[50:53], v[16:17], off offset:1664
	global_load_dwordx4 v[54:57], v[18:19], off offset:-320
	global_load_dwordx4 v[58:61], v[16:17], off offset:1728
	global_load_dwordx4 v[62:65], v[18:19], off offset:-256
	global_load_dwordx4 v[66:69], v[16:17], off offset:1792
	global_load_dwordx4 v[70:73], v[18:19], off offset:-192
	global_load_dwordx4 v[74:77], v[16:17], off offset:1856
	global_load_dwordx4 v[78:81], v[18:19], off offset:-128
	global_load_dwordx4 v[82:85], v[16:17], off offset:1920
	global_load_dwordx4 v[86:89], v[18:19], off offset:-64
	global_load_dwordx4 v[90:93], v[16:17], off offset:1984
	global_load_dwordx4 v[94:97], v[18:19], off
	global_load_dwordx4 v[98:101], v[16:17], off offset:2048
	global_load_dwordx4 v[102:105], v[18:19], off offset:64
	global_load_dwordx4 v[106:109], v[16:17], off offset:2112
	global_load_dwordx4 v[110:113], v[18:19], off offset:128
	global_load_dwordx4 v[114:117], v[16:17], off offset:2176
	global_load_dwordx4 v[118:121], v[18:19], off offset:192
	global_load_dwordx4 v[122:125], v[16:17], off offset:2240
	global_load_dwordx4 v[126:129], v[18:19], off offset:256
	global_load_dwordx4 v[130:133], v[16:17], off offset:2304
	global_load_dwordx4 v[134:137], v[18:19], off offset:320
	global_load_dwordx4 v[138:141], v[16:17], off offset:2368
	global_load_dwordx4 v[142:145], v[18:19], off offset:384
	global_load_dwordx4 v[146:149], v[16:17], off offset:2432
	global_load_dwordx4 v[150:153], v[18:19], off offset:448
	global_load_dwordx4 v[154:157], v[16:17], off offset:2496
	s_cmpk_eq_i32 s42, 0x800
	s_waitcnt vmcnt(30)
	v_mfma_f32_16x16x32_bf16 v[2:5], v[30:33], v[34:37], v[2:5]
	s_waitcnt vmcnt(28)
	v_mfma_f32_16x16x32_bf16 v[2:5], v[38:41], v[42:45], v[2:5]
	s_waitcnt vmcnt(26)
	v_mfma_f32_16x16x32_bf16 v[2:5], v[46:49], v[50:53], v[2:5]
	s_waitcnt vmcnt(24)
	v_mfma_f32_16x16x32_bf16 v[2:5], v[54:57], v[58:61], v[2:5]
	s_waitcnt vmcnt(22)
	v_mfma_f32_16x16x32_bf16 v[2:5], v[62:65], v[66:69], v[2:5]
	s_waitcnt vmcnt(20)
	v_mfma_f32_16x16x32_bf16 v[2:5], v[70:73], v[74:77], v[2:5]
	s_waitcnt vmcnt(18)
	v_mfma_f32_16x16x32_bf16 v[2:5], v[78:81], v[82:85], v[2:5]
	s_waitcnt vmcnt(16)
	v_mfma_f32_16x16x32_bf16 v[2:5], v[86:89], v[90:93], v[2:5]
	s_waitcnt vmcnt(14)
	v_mfma_f32_16x16x32_bf16 v[2:5], v[94:97], v[98:101], v[2:5]
	s_waitcnt vmcnt(12)
	v_mfma_f32_16x16x32_bf16 v[2:5], v[102:105], v[106:109], v[2:5]
	s_waitcnt vmcnt(10)
	v_mfma_f32_16x16x32_bf16 v[2:5], v[110:113], v[114:117], v[2:5]
	s_waitcnt vmcnt(8)
	v_mfma_f32_16x16x32_bf16 v[2:5], v[118:121], v[122:125], v[2:5]
	s_waitcnt vmcnt(6)
	v_mfma_f32_16x16x32_bf16 v[2:5], v[126:129], v[130:133], v[2:5]
	s_waitcnt vmcnt(4)
	v_mfma_f32_16x16x32_bf16 v[2:5], v[134:137], v[138:141], v[2:5]
	s_waitcnt vmcnt(2)
	v_mfma_f32_16x16x32_bf16 v[2:5], v[142:145], v[146:149], v[2:5]
	s_waitcnt vmcnt(0)
	v_mfma_f32_16x16x32_bf16 v[2:5], v[150:153], v[154:157], v[2:5]
	s_cbranch_scc0 .LBB0_514
	s_and_saveexec_b64 s[42:43], s[0:1]
	s_cbranch_execz .LBB0_512
	v_lshl_or_b32 v14, v20, 4, v21
	v_ashrrev_i32_e32 v15, 31, v14
	v_lshl_add_u64 v[16:17], v[14:15], 3, s[36:37]
	global_load_dwordx2 v[16:17], v[16:17], off
	v_lshlrev_b64 v[14:15], 5, v[14:15]
	v_lshl_add_u64 v[14:15], v[6:7], 0, v[14:15]
	s_waitcnt vmcnt(0)
	v_ffbh_u32_e32 v0, v17
	v_min_u32_e32 v0, 32, v0
	v_lshlrev_b64 v[16:17], v0, v[16:17]
	v_min_u32_e32 v11, 1, v16
	v_or_b32_e32 v11, v17, v11
	v_cvt_f32_u32_e32 v11, v11
	v_sub_u32_e32 v0, 32, v0
	v_ldexp_f32 v0, v11, v0
	v_fmamk_f32 v0, v0, 0x30800000, v162
	v_mul_f32_e32 v11, 0x4b800000, v0
	v_cmp_gt_f32_e32 vcc, s95, v0
	s_nop 1
	v_cndmask_b32_e32 v0, v0, v11, vcc
	v_rsq_f32_e32 v0, v0
	s_nop 0
	v_mul_f32_e32 v11, 0x45800000, v0
	v_cndmask_b32_e32 v0, v0, v11, vcc
	v_pk_mul_f32 v[4:5], v[4:5], v[0:1] op_sel_hi:[1,0]
	v_pk_mul_f32 v[2:3], v[2:3], v[0:1] op_sel_hi:[1,0]
	global_store_dwordx4 v[14:15], v[2:5], off
	s_branch .LBB0_512
